# 256x256 GEMM K-loops: the next half-tile's fragment reads whose registers are already free are issued right after the K-tile barrier (3 MFMAs earlier)
# baseline (speedup 1.0000x reference)
; DI int fresh_tid(const Params& p) { int t = p.wave_u * 64 + (int)__builtin_amdgcn_mbcnt_hi(~0u, __builtin_amdgcn_mbcnt_lo(~0u, 0u)); asm volatile("" : "+v"(t)); return t; }
; #define G3_LDA(buf, kt, i) __builtin_amdgcn_global_load_lds((const unsigned*)(ga + (size_t)((i) * 64) * lda + (kt) * 64), (lds_u32*)(sdst + (buf) * STAGE + (i) * 8192), 16, 0, 0)
; #define G3_LDB(buf, kt, i) __builtin_amdgcn_global_load_lds((const unsigned*)(gb + (size_t)((i) * 64) * ldb + (kt) * 64), (lds_u32*)(sdst + (buf) * STAGE + B_OFF + (i) * 8192), 16, 0, 0)
; DI void gemm3_mainloop(const int wave8, const int lane, const bf16_t* __restrict__ A, int lda, const bf16_t* __restrict__ Bt, int ldb, int K,
;                        unsigned char* smem, f32x4 (&acc)[8][4]) {
;     constexpr int STAGE = 512 * 128, B_OFF = 256 * 128;
;     const int fr = lane & 15, fq = lane >> 4, wm = wave8 >> 2, wn = wave8 & 3;
;     const int t512 = wave8 * 64 + lane;
; #pragma unroll
;     for (int i = 0; i < 8; ++i)
; #pragma unroll
;         for (int j = 0; j < 4; ++j) acc[i][j] = (f32x4){0.f, 0.f, 0.f, 0.f};
;     const int nk = K / 64;
;     const int srow = t512 >> 3, ssc = (t512 & 7) ^ ((srow >> 1) & 7);
;     const bf16_t* ga = A + (size_t)srow * lda + ssc * 8;
;     const bf16_t* gb = Bt + (size_t)srow * ldb + ssc * 8;
;     unsigned char* sdst = smem + wave8 * 1024;
;     ...
;     const int sw = (fr >> 1) & 7;
;     ...
;     asm volatile("s_waitcnt vmcnt(0)" ::: "memory");
;     G3_LDA(0, 0, 0); G3_LDA(0, 0, 1); G3_LDA(0, 0, 2); G3_LDA(0, 0, 3); G3_LDB(0, 0, 0); G3_LDB(0, 0, 1); G3_LDB(0, 0, 2); G3_LDB(0, 0, 3);
;     asm volatile("s_waitcnt vmcnt(0)" ::: "memory");
;     __builtin_amdgcn_s_barrier();
; DI void phase1(const Params& p, unsigned char* smem) {
;     ...
;     for_tiles3(T_ / 256, NPAD / 256, [&](int mt, int nt) {
;         const int lane = fresh_tid(p) & 63, fr = lane & 15, fq = lane >> 4, wm = p.wave8 >> 2, wn = p.wave8 & 3;
;         f32x4 acc[8][4];
;         gemm3_mainloop(p.wave8, lane, xn + (size_t)mt * 256 * LDK, LDK, wt + (size_t)nt * 256 * LDK, LDK, DM, smem, acc);
.LBB0_89:
	s_and_b32 s4, s53, 7
	s_add_i32 s4, s51, s4
	s_mul_i32 s18, s4, 0x108000
	s_and_b32 s4, s74, 7
	v_mov_b32_e32 v147, v227
	s_or_b32 s4, s4, s51
	s_ashr_i32 s5, s74, 3
	s_add_i32 s5, s5, s52
	v_and_b32_e32 v146, 63, v147
	s_mul_i32 s6, s4, 0x108000
	v_or_b32_e32 v0, s86, v146
	s_add_u32 s6, s11, s6
	v_lshrrev_b32_e32 v3, 4, v0
	s_addc_u32 s7, s47, 0
	s_mul_i32 s37, s5, 0x108000
	v_bitop3_b32 v4, v3, v147, 63 bitop3:0x78
	s_mul_hi_i32 s36, s5, 0x108000
	s_add_u32 s8, s3, s37
	v_ashrrev_i32_e32 v2, 3, v0
	v_mov_b64_e32 v[0:1], s[6:7]
	v_lshlrev_b32_e32 v4, 4, v4
	s_addc_u32 s9, s15, s36
	v_mad_i64_i32 v[0:1], s[6:7], v2, s45, v[0:1]
	v_and_b32_e32 v132, 0x70, v4
	v_lshl_add_u64 v[134:135], v[0:1], 0, v[132:133]
	v_mov_b64_e32 v[0:1], s[8:9]
	s_mov_b32 m0, s0
	v_mad_i64_i32 v[0:1], s[6:7], v2, s45, v[0:1]
	s_waitcnt vmcnt(0)
	v_lshl_add_u64 v[136:137], v[0:1], 0, v[132:133]
	global_load_lds_dwordx4 v[134:135], off
	v_lshl_add_u64 v[0:1], v[134:135], 0, s[22:23]
	s_mov_b32 m0, s55
	v_bfe_u32 v145, v147, 4, 2
	global_load_lds_dwordx4 v[0:1], off
	v_lshl_add_u64 v[0:1], v[134:135], 0, s[24:25]
	s_mov_b32 m0, s87
	v_lshrrev_b32_e32 v4, 1, v147
	global_load_lds_dwordx4 v[0:1], off
	v_lshl_add_u64 v[0:1], v[134:135], 0, s[26:27]
	s_mov_b32 m0, s69
	s_waitcnt lgkmcnt(0)
	v_bfe_u32 v5, v147, 1, 3
	global_load_lds_dwordx4 v[0:1], off
	s_mov_b32 m0, s68
	v_lshl_add_u64 v[0:1], v[136:137], 0, s[22:23]
	global_load_lds_dwordx4 v[136:137], off
	s_mov_b32 m0, s39
	s_add_i32 s6, 0, 0x10000
	global_load_lds_dwordx4 v[0:1], off
	v_lshl_add_u64 v[0:1], v[136:137], 0, s[24:25]
	s_mov_b32 m0, s38
	v_mov_b32_e32 v28, 0
	global_load_lds_dwordx4 v[0:1], off
	v_lshl_add_u64 v[0:1], v[136:137], 0, s[26:27]
	s_mov_b32 m0, s1
	v_mov_b32_e32 v29, v28
	global_load_lds_dwordx4 v[0:1], off
	v_bitop3_b32 v0, v4, v145, 7 bitop3:0x6c
	v_lshlrev_b32_e32 v0, 4, v0
	v_bitop3_b32 v1, v145, v5, 4 bitop3:0x36
	v_add_u32_e32 v4, 0, v0
	v_lshlrev_b32_e32 v1, 4, v1
	v_add_u32_e32 v6, s83, v0
	v_add_u32_e32 v7, s6, v0
	v_lshlrev_b32_e32 v0, 7, v147
	v_add_u32_e32 v9, s6, v1
	v_and_b32_e32 v0, 0x780, v0
	s_add_u32 s6, s72, s18
	v_or_b32_e32 v10, s90, v0
	v_or_b32_e32 v11, s91, v0
	v_bitop3_b32 v0, v3, 7, v146 bitop3:0x48
	s_addc_u32 s7, s73, 0
	v_add_u32_e32 v5, 0, v1
	v_add_u32_e32 v8, s83, v1
	v_lshlrev_b32_e32 v132, 4, v0
	v_mov_b64_e32 v[0:1], s[6:7]
	v_mad_i64_i32 v[138:139], s[6:7], v2, s45, v[0:1]
	s_add_u32 s6, s72, s37
	s_addc_u32 s7, s73, s36
	s_waitcnt vmcnt(0)
	v_mov_b64_e32 v[0:1], s[6:7]
	v_mad_i64_i32 v[140:141], s[6:7], v2, s45, v[0:1]
	s_mov_b32 s6, 0
	v_add_u32_e32 v148, v4, v10
	v_add_u32_e32 v149, v4, v11
	v_add_u32_e32 v150, v5, v10
	v_add_u32_e32 v151, v5, v11
	v_add_u32_e32 v152, v6, v10
	v_add_u32_e32 v153, v7, v11
	v_add_u32_e32 v154, v8, v10
	v_add_u32_e32 v155, v9, v11
	v_mov_b32_e32 v30, v28
	v_mov_b32_e32 v31, v28
	v_mov_b32_e32 v4, v28
	v_mov_b32_e32 v5, v28
	v_mov_b32_e32 v6, v28
	v_mov_b32_e32 v7, v28
	v_mov_b32_e32 v8, v28
	v_mov_b32_e32 v9, v28
	v_mov_b32_e32 v10, v28
	v_mov_b32_e32 v11, v28
	v_mov_b32_e32 v0, v28
	v_mov_b32_e32 v1, v28
	v_mov_b32_e32 v2, v28
	v_mov_b32_e32 v3, v28
	v_mov_b32_e32 v16, v28
	v_mov_b32_e32 v17, v28
	v_mov_b32_e32 v18, v28
	v_mov_b32_e32 v19, v28
	v_mov_b32_e32 v20, v28
	v_mov_b32_e32 v21, v28
	v_mov_b32_e32 v22, v28
	v_mov_b32_e32 v23, v28
	v_mov_b32_e32 v24, v28
	v_mov_b32_e32 v25, v28
	v_mov_b32_e32 v26, v28
	v_mov_b32_e32 v27, v28
	v_mov_b32_e32 v12, v28
	v_mov_b32_e32 v13, v28
	v_mov_b32_e32 v14, v28
	v_mov_b32_e32 v15, v28
	v_mov_b32_e32 v36, v28
	v_mov_b32_e32 v37, v28
	v_mov_b32_e32 v38, v28
	v_mov_b32_e32 v39, v28
	v_mov_b32_e32 v40, v28
	v_mov_b32_e32 v41, v28
	v_mov_b32_e32 v42, v28
	v_mov_b32_e32 v43, v28
	v_mov_b32_e32 v44, v28
	v_mov_b32_e32 v45, v28
	v_mov_b32_e32 v46, v28
	v_mov_b32_e32 v47, v28
	v_mov_b32_e32 v32, v28
	v_mov_b32_e32 v33, v28
	v_mov_b32_e32 v34, v28
	v_mov_b32_e32 v35, v28
	v_mov_b32_e32 v52, v28
	v_mov_b32_e32 v53, v28
	v_mov_b32_e32 v54, v28
	v_mov_b32_e32 v55, v28
	v_mov_b32_e32 v56, v28
	v_mov_b32_e32 v57, v28
	v_mov_b32_e32 v58, v28
	v_mov_b32_e32 v59, v28
	v_mov_b32_e32 v60, v28
	v_mov_b32_e32 v61, v28
	v_mov_b32_e32 v62, v28
	v_mov_b32_e32 v63, v28
	v_mov_b32_e32 v48, v28
	v_mov_b32_e32 v49, v28
	v_mov_b32_e32 v50, v28
	v_mov_b32_e32 v51, v28
	v_mov_b32_e32 v68, v28
	v_mov_b32_e32 v69, v28
	v_mov_b32_e32 v70, v28
	v_mov_b32_e32 v71, v28
	v_mov_b32_e32 v72, v28
	v_mov_b32_e32 v73, v28
	v_mov_b32_e32 v74, v28
	v_mov_b32_e32 v75, v28
	v_mov_b32_e32 v76, v28
	v_mov_b32_e32 v77, v28
	v_mov_b32_e32 v78, v28
	v_mov_b32_e32 v79, v28
	v_mov_b32_e32 v64, v28
	v_mov_b32_e32 v65, v28
	v_mov_b32_e32 v66, v28
	v_mov_b32_e32 v67, v28
	v_mov_b32_e32 v84, v28
	v_mov_b32_e32 v85, v28
	v_mov_b32_e32 v86, v28
	v_mov_b32_e32 v87, v28
	v_mov_b32_e32 v88, v28
	v_mov_b32_e32 v89, v28
	v_mov_b32_e32 v90, v28
	v_mov_b32_e32 v91, v28
	v_mov_b32_e32 v92, v28
	v_mov_b32_e32 v93, v28
	v_mov_b32_e32 v94, v28
	v_mov_b32_e32 v95, v28
	v_mov_b32_e32 v80, v28
	v_mov_b32_e32 v81, v28
	v_mov_b32_e32 v82, v28
	v_mov_b32_e32 v83, v28
	v_mov_b32_e32 v100, v28
	v_mov_b32_e32 v101, v28
	v_mov_b32_e32 v102, v28
	v_mov_b32_e32 v103, v28
	v_mov_b32_e32 v104, v28
	v_mov_b32_e32 v105, v28
	v_mov_b32_e32 v106, v28
	v_mov_b32_e32 v107, v28
	v_mov_b32_e32 v108, v28
	v_mov_b32_e32 v109, v28
	v_mov_b32_e32 v110, v28
	v_mov_b32_e32 v111, v28
	v_mov_b32_e32 v96, v28
	v_mov_b32_e32 v97, v28
	v_mov_b32_e32 v98, v28
	v_mov_b32_e32 v99, v28
	v_mov_b32_e32 v116, v28
	v_mov_b32_e32 v117, v28
	v_mov_b32_e32 v118, v28
	v_mov_b32_e32 v119, v28
	v_mov_b32_e32 v120, v28
	v_mov_b32_e32 v121, v28
	v_mov_b32_e32 v122, v28
	v_mov_b32_e32 v123, v28
	v_mov_b32_e32 v124, v28
	v_mov_b32_e32 v125, v28
	v_mov_b32_e32 v126, v28
	v_mov_b32_e32 v127, v28
	v_mov_b32_e32 v112, v28
	v_mov_b32_e32 v113, v28
	v_mov_b32_e32 v114, v28
	v_mov_b32_e32 v115, v28
	s_barrier
	ds_read_b128 v[168:171], v149
	ds_read_b128 v[156:159], v148 offset:34816
	ds_read_b128 v[172:175], v149 offset:2048
	ds_read_b128 v[176:179], v149 offset:4096
	ds_read_b128 v[180:183], v149 offset:6144
	ds_read_b128 v[184:187], v149 offset:8192
	ds_read_b128 v[188:191], v149 offset:10240
	ds_read_b128 v[192:195], v149 offset:12288
; DI void gemm3_mainloop(const int wave8, const int lane, const bf16_t* __restrict__ A, int lda, const bf16_t* __restrict__ Bt, int ldb, int K,
;                        unsigned char* smem, f32x4 (&acc)[8][4]) {
;     ...
;     const int sw = (fr >> 1) & 7;
.LBB0_90:
	ds_read_b128 v[128:131], v148 offset:32768
	ds_read_b128 v[160:163], v148 offset:36864
	ds_read_b128 v[164:167], v148 offset:38912
	ds_read_b128 v[196:199], v149 offset:14336
	s_waitcnt lgkmcnt(3)
	v_mfma_f32_16x16x32_bf16 v[112:115], v[128:131], v[168:171], v[112:115]
	s_mov_b64 s[8:9], 0x19dc5080
	s_mov_b32 m0, s88
	s_add_i32 s18, s6, 1
	v_mfma_f32_16x16x32_bf16 v[124:127], v[156:159], v[168:171], v[124:127]
	s_add_i32 s7, s6, 2
	s_cmp_lt_u32 s6, 30
	s_waitcnt lgkmcnt(2)
	v_mfma_f32_16x16x32_bf16 v[120:123], v[160:163], v[168:171], v[120:123]
	s_waitcnt lgkmcnt(1)
	v_mfma_f32_16x16x32_bf16 v[116:119], v[164:167], v[168:171], v[116:119]
	v_lshl_add_u64 v[168:169], v[138:139], 0, v[132:133]
	v_lshl_add_u64 v[170:171], v[168:169], 0, s[8:9]
	s_mov_b64 s[8:9], 0x19e07080
	global_load_lds_dwordx4 v[170:171], off
	v_lshl_add_u64 v[170:171], v[168:169], 0, s[8:9]
	s_mov_b32 m0, s92
	s_mov_b64 s[8:9], 0x19e49080
	v_mfma_f32_16x16x32_bf16 v[96:99], v[128:131], v[172:175], v[96:99]
	v_lshl_add_u64 v[138:139], v[138:139], 0, s[34:35]
	v_mfma_f32_16x16x32_bf16 v[108:111], v[156:159], v[172:175], v[108:111]
	v_mfma_f32_16x16x32_bf16 v[104:107], v[160:163], v[172:175], v[104:107]
	v_mfma_f32_16x16x32_bf16 v[100:103], v[164:167], v[172:175], v[100:103]
	global_load_lds_dwordx4 v[170:171], off
	v_lshl_add_u64 v[170:171], v[168:169], 0, s[8:9]
	s_mov_b32 m0, s93
	s_mov_b64 s[8:9], 0x19e8b080
	v_mfma_f32_16x16x32_bf16 v[80:83], v[128:131], v[176:179], v[80:83]
	v_lshl_add_u64 v[168:169], v[168:169], 0, s[8:9]
	s_mov_b64 s[8:9], 0x245080
	v_mfma_f32_16x16x32_bf16 v[92:95], v[156:159], v[176:179], v[92:95]
	v_mfma_f32_16x16x32_bf16 v[88:91], v[160:163], v[176:179], v[88:91]
	v_mfma_f32_16x16x32_bf16 v[84:87], v[164:167], v[176:179], v[84:87]
	global_load_lds_dwordx4 v[170:171], off
	s_mov_b32 m0, s94
	v_mfma_f32_16x16x32_bf16 v[64:67], v[128:131], v[180:183], v[64:67]
	v_mfma_f32_16x16x32_bf16 v[76:79], v[156:159], v[180:183], v[76:79]
	v_mfma_f32_16x16x32_bf16 v[72:75], v[160:163], v[180:183], v[72:75]
	v_mfma_f32_16x16x32_bf16 v[68:71], v[164:167], v[180:183], v[68:71]
	global_load_lds_dwordx4 v[168:169], off
	s_mov_b32 m0, s89
	v_mfma_f32_16x16x32_bf16 v[48:51], v[128:131], v[184:187], v[48:51]
	v_mfma_f32_16x16x32_bf16 v[60:63], v[156:159], v[184:187], v[60:63]
	v_mfma_f32_16x16x32_bf16 v[56:59], v[160:163], v[184:187], v[56:59]
	v_mfma_f32_16x16x32_bf16 v[52:55], v[164:167], v[184:187], v[52:55]
	v_mfma_f32_16x16x32_bf16 v[32:35], v[128:131], v[188:191], v[32:35]
	v_mfma_f32_16x16x32_bf16 v[44:47], v[156:159], v[188:191], v[44:47]
	v_mfma_f32_16x16x32_bf16 v[40:43], v[160:163], v[188:191], v[40:43]
	v_mfma_f32_16x16x32_bf16 v[36:39], v[164:167], v[188:191], v[36:39]
	v_mfma_f32_16x16x32_bf16 v[12:15], v[128:131], v[192:195], v[12:15]
	v_mfma_f32_16x16x32_bf16 v[24:27], v[156:159], v[192:195], v[24:27]
	v_mfma_f32_16x16x32_bf16 v[20:23], v[160:163], v[192:195], v[20:23]
	v_mfma_f32_16x16x32_bf16 v[16:19], v[164:167], v[192:195], v[16:19]
	s_waitcnt lgkmcnt(0)
	v_mfma_f32_16x16x32_bf16 v[0:3], v[128:131], v[196:199], v[0:3]
	v_mfma_f32_16x16x32_bf16 v[8:11], v[156:159], v[196:199], v[8:11]
	v_mfma_f32_16x16x32_bf16 v[4:7], v[160:163], v[196:199], v[4:7]
	v_mfma_f32_16x16x32_bf16 v[28:31], v[164:167], v[196:199], v[28:31]
	ds_read_b128 v[128:131], v150 offset:32768
	ds_read_b128 v[168:171], v151
	ds_read_b128 v[156:159], v150 offset:34816
	ds_read_b128 v[160:163], v150 offset:36864
	ds_read_b128 v[164:167], v150 offset:38912
	ds_read_b128 v[172:175], v151 offset:2048
	ds_read_b128 v[176:179], v151 offset:4096
	ds_read_b128 v[180:183], v151 offset:6144
	ds_read_b128 v[184:187], v151 offset:8192
	ds_read_b128 v[188:191], v151 offset:10240
	ds_read_b128 v[192:195], v151 offset:12288
	ds_read_b128 v[196:199], v151 offset:14336
	s_waitcnt lgkmcnt(10)
	v_mfma_f32_16x16x32_bf16 v[112:115], v[128:131], v[168:171], v[112:115]
	s_waitcnt lgkmcnt(9)
	v_mfma_f32_16x16x32_bf16 v[124:127], v[156:159], v[168:171], v[124:127]
	s_waitcnt lgkmcnt(8)
	v_mfma_f32_16x16x32_bf16 v[120:123], v[160:163], v[168:171], v[120:123]
	s_waitcnt lgkmcnt(7)
	v_mfma_f32_16x16x32_bf16 v[116:119], v[164:167], v[168:171], v[116:119]
	v_lshl_add_u64 v[168:169], v[140:141], 0, v[132:133]
	v_lshl_add_u64 v[170:171], v[168:169], 0, s[8:9]
	s_mov_b64 s[8:9], 0x287080
	global_load_lds_dwordx4 v[170:171], off
	v_lshl_add_u64 v[170:171], v[168:169], 0, s[8:9]
	s_mov_b32 m0, s95
	s_waitcnt lgkmcnt(6)
	v_mfma_f32_16x16x32_bf16 v[96:99], v[128:131], v[172:175], v[96:99]
	s_cselect_b64 s[8:9], -1, 0
	s_and_b64 vcc, s[8:9], exec
	s_cselect_b32 s6, s7, s18
	v_mfma_f32_16x16x32_bf16 v[108:111], v[156:159], v[172:175], v[108:111]
	s_lshl_b32 s18, s6, 7
	v_lshl_add_u64 v[140:141], v[140:141], 0, s[34:35]
	s_mov_b32 s6, s7
	v_mfma_f32_16x16x32_bf16 v[104:107], v[160:163], v[172:175], v[104:107]
	v_mfma_f32_16x16x32_bf16 v[100:103], v[164:167], v[172:175], v[100:103]
	global_load_lds_dwordx4 v[170:171], off
	v_lshl_add_u64 v[170:171], v[168:169], 0, s[28:29]
	s_mov_b32 m0, s96
	s_waitcnt lgkmcnt(5)
	v_mfma_f32_16x16x32_bf16 v[80:83], v[128:131], v[176:179], v[80:83]
	v_lshl_add_u64 v[168:169], v[168:169], 0, s[30:31]
	v_mfma_f32_16x16x32_bf16 v[92:95], v[156:159], v[176:179], v[92:95]
	v_mfma_f32_16x16x32_bf16 v[88:91], v[160:163], v[176:179], v[88:91]
	v_mfma_f32_16x16x32_bf16 v[84:87], v[164:167], v[176:179], v[84:87]
	global_load_lds_dwordx4 v[170:171], off
	s_mov_b32 m0, s97
	s_waitcnt lgkmcnt(4)
	v_mfma_f32_16x16x32_bf16 v[64:67], v[128:131], v[180:183], v[64:67]
	v_mfma_f32_16x16x32_bf16 v[76:79], v[156:159], v[180:183], v[76:79]
	v_mfma_f32_16x16x32_bf16 v[72:75], v[160:163], v[180:183], v[72:75]
	v_mfma_f32_16x16x32_bf16 v[68:71], v[164:167], v[180:183], v[68:71]
	global_load_lds_dwordx4 v[168:169], off
	s_waitcnt lgkmcnt(3)
	v_mfma_f32_16x16x32_bf16 v[48:51], v[128:131], v[184:187], v[48:51]
	s_mov_b32 m0, s0
	v_mfma_f32_16x16x32_bf16 v[60:63], v[156:159], v[184:187], v[60:63]
	v_mfma_f32_16x16x32_bf16 v[56:59], v[160:163], v[184:187], v[56:59]
	v_mfma_f32_16x16x32_bf16 v[52:55], v[164:167], v[184:187], v[52:55]
	s_waitcnt lgkmcnt(2)
	v_mfma_f32_16x16x32_bf16 v[32:35], v[128:131], v[188:191], v[32:35]
	v_mfma_f32_16x16x32_bf16 v[44:47], v[156:159], v[188:191], v[44:47]
	v_mfma_f32_16x16x32_bf16 v[40:43], v[160:163], v[188:191], v[40:43]
	v_mfma_f32_16x16x32_bf16 v[36:39], v[164:167], v[188:191], v[36:39]
	s_waitcnt lgkmcnt(1)
	v_mfma_f32_16x16x32_bf16 v[12:15], v[128:131], v[192:195], v[12:15]
	v_mfma_f32_16x16x32_bf16 v[24:27], v[156:159], v[192:195], v[24:27]
	v_mfma_f32_16x16x32_bf16 v[20:23], v[160:163], v[192:195], v[20:23]
	v_mfma_f32_16x16x32_bf16 v[16:19], v[164:167], v[192:195], v[16:19]
	s_waitcnt lgkmcnt(0)
	v_mfma_f32_16x16x32_bf16 v[0:3], v[128:131], v[196:199], v[0:3]
	s_waitcnt vmcnt(0)
	s_barrier
; DI void gemm3_mainloop(const int wave8, const int lane, const bf16_t* __restrict__ A, int lda, const bf16_t* __restrict__ Bt, int ldb, int K,
;                        unsigned char* smem, f32x4 (&acc)[8][4]) {
;     ...
;     const int sw = (fr >> 1) & 7;
	ds_read_b128 v[128:131], v152
	ds_read_b128 v[168:171], v153
	ds_read_b128 v[172:175], v153 offset:2048
	ds_read_b128 v[176:179], v153 offset:4096
	ds_read_b128 v[180:183], v153 offset:6144
	ds_read_b128 v[184:187], v153 offset:8192
	ds_read_b128 v[188:191], v153 offset:10240
	ds_read_b128 v[192:195], v153 offset:12288
	v_mfma_f32_16x16x32_bf16 v[8:11], v[156:159], v[196:199], v[8:11]
	v_mfma_f32_16x16x32_bf16 v[4:7], v[160:163], v[196:199], v[4:7]
	v_mfma_f32_16x16x32_bf16 v[28:31], v[164:167], v[196:199], v[28:31]
	ds_read_b128 v[156:159], v152 offset:2048
	ds_read_b128 v[160:163], v152 offset:4096
	ds_read_b128 v[164:167], v152 offset:6144
	ds_read_b128 v[196:199], v153 offset:14336
	s_waitcnt lgkmcnt(10)
	v_mfma_f32_16x16x32_bf16 v[112:115], v[128:131], v[168:171], v[112:115]
	s_waitcnt lgkmcnt(3)
	v_mfma_f32_16x16x32_bf16 v[124:127], v[156:159], v[168:171], v[124:127]
	s_waitcnt lgkmcnt(2)
	v_mfma_f32_16x16x32_bf16 v[120:123], v[160:163], v[168:171], v[120:123]
	s_waitcnt lgkmcnt(1)
	v_mfma_f32_16x16x32_bf16 v[116:119], v[164:167], v[168:171], v[116:119]
	v_lshl_add_u64 v[168:169], v[134:135], 0, s[18:19]
	global_load_lds_dwordx4 v[168:169], off
	v_lshl_add_u64 v[170:171], v[168:169], 0, s[22:23]
	s_mov_b32 m0, s55
	v_mfma_f32_16x16x32_bf16 v[96:99], v[128:131], v[172:175], v[96:99]
	v_mfma_f32_16x16x32_bf16 v[108:111], v[156:159], v[172:175], v[108:111]
	v_mfma_f32_16x16x32_bf16 v[104:107], v[160:163], v[172:175], v[104:107]
	v_mfma_f32_16x16x32_bf16 v[100:103], v[164:167], v[172:175], v[100:103]
	global_load_lds_dwordx4 v[170:171], off
	v_lshl_add_u64 v[170:171], v[168:169], 0, s[24:25]
	s_mov_b32 m0, s87
	v_mfma_f32_16x16x32_bf16 v[80:83], v[128:131], v[176:179], v[80:83]
	v_lshl_add_u64 v[168:169], v[168:169], 0, s[26:27]
	v_mfma_f32_16x16x32_bf16 v[92:95], v[156:159], v[176:179], v[92:95]
	v_mfma_f32_16x16x32_bf16 v[88:91], v[160:163], v[176:179], v[88:91]
	v_mfma_f32_16x16x32_bf16 v[84:87], v[164:167], v[176:179], v[84:87]
	global_load_lds_dwordx4 v[170:171], off
	s_mov_b32 m0, s69
	v_mfma_f32_16x16x32_bf16 v[64:67], v[128:131], v[180:183], v[64:67]
	v_mfma_f32_16x16x32_bf16 v[76:79], v[156:159], v[180:183], v[76:79]
	v_mfma_f32_16x16x32_bf16 v[72:75], v[160:163], v[180:183], v[72:75]
	v_mfma_f32_16x16x32_bf16 v[68:71], v[164:167], v[180:183], v[68:71]
	global_load_lds_dwordx4 v[168:169], off
	s_mov_b32 m0, s68
	v_mfma_f32_16x16x32_bf16 v[48:51], v[128:131], v[184:187], v[48:51]
	v_mfma_f32_16x16x32_bf16 v[60:63], v[156:159], v[184:187], v[60:63]
	v_mfma_f32_16x16x32_bf16 v[56:59], v[160:163], v[184:187], v[56:59]
	v_mfma_f32_16x16x32_bf16 v[52:55], v[164:167], v[184:187], v[52:55]
	v_mfma_f32_16x16x32_bf16 v[32:35], v[128:131], v[188:191], v[32:35]
	v_mfma_f32_16x16x32_bf16 v[44:47], v[156:159], v[188:191], v[44:47]
	v_mfma_f32_16x16x32_bf16 v[40:43], v[160:163], v[188:191], v[40:43]
	v_mfma_f32_16x16x32_bf16 v[36:39], v[164:167], v[188:191], v[36:39]
	v_mfma_f32_16x16x32_bf16 v[12:15], v[128:131], v[192:195], v[12:15]
	v_mfma_f32_16x16x32_bf16 v[24:27], v[156:159], v[192:195], v[24:27]
	v_mfma_f32_16x16x32_bf16 v[20:23], v[160:163], v[192:195], v[20:23]
	v_mfma_f32_16x16x32_bf16 v[16:19], v[164:167], v[192:195], v[16:19]
	s_waitcnt lgkmcnt(0)
	v_mfma_f32_16x16x32_bf16 v[0:3], v[128:131], v[196:199], v[0:3]
	v_mfma_f32_16x16x32_bf16 v[8:11], v[156:159], v[196:199], v[8:11]
	v_mfma_f32_16x16x32_bf16 v[4:7], v[160:163], v[196:199], v[4:7]
	v_mfma_f32_16x16x32_bf16 v[28:31], v[164:167], v[196:199], v[28:31]
	ds_read_b128 v[156:159], v154
	ds_read_b128 v[168:171], v155
	ds_read_b128 v[160:163], v154 offset:2048
	ds_read_b128 v[164:167], v154 offset:4096
	ds_read_b128 v[128:131], v154 offset:6144
	ds_read_b128 v[172:175], v155 offset:2048
	ds_read_b128 v[176:179], v155 offset:4096
	ds_read_b128 v[180:183], v155 offset:6144
	ds_read_b128 v[184:187], v155 offset:8192
	ds_read_b128 v[188:191], v155 offset:10240
	ds_read_b128 v[192:195], v155 offset:12288
	ds_read_b128 v[196:199], v155 offset:14336
	s_waitcnt lgkmcnt(10)
	v_mfma_f32_16x16x32_bf16 v[112:115], v[156:159], v[168:171], v[112:115]
	s_waitcnt lgkmcnt(9)
	v_mfma_f32_16x16x32_bf16 v[124:127], v[160:163], v[168:171], v[124:127]
	s_waitcnt lgkmcnt(8)
	v_mfma_f32_16x16x32_bf16 v[120:123], v[164:167], v[168:171], v[120:123]
	s_waitcnt lgkmcnt(7)
	v_mfma_f32_16x16x32_bf16 v[116:119], v[128:131], v[168:171], v[116:119]
	v_lshl_add_u64 v[168:169], v[136:137], 0, s[18:19]
	global_load_lds_dwordx4 v[168:169], off
	v_lshl_add_u64 v[170:171], v[168:169], 0, s[22:23]
	s_mov_b32 m0, s39
	s_waitcnt lgkmcnt(6)
	v_mfma_f32_16x16x32_bf16 v[96:99], v[156:159], v[172:175], v[96:99]
	v_mfma_f32_16x16x32_bf16 v[108:111], v[160:163], v[172:175], v[108:111]
	v_mfma_f32_16x16x32_bf16 v[104:107], v[164:167], v[172:175], v[104:107]
	v_mfma_f32_16x16x32_bf16 v[100:103], v[128:131], v[172:175], v[100:103]
	global_load_lds_dwordx4 v[170:171], off
	v_lshl_add_u64 v[170:171], v[168:169], 0, s[24:25]
	s_mov_b32 m0, s38
	s_waitcnt lgkmcnt(5)
	v_mfma_f32_16x16x32_bf16 v[80:83], v[156:159], v[176:179], v[80:83]
	v_lshl_add_u64 v[168:169], v[168:169], 0, s[26:27]
	v_mfma_f32_16x16x32_bf16 v[92:95], v[160:163], v[176:179], v[92:95]
	v_mfma_f32_16x16x32_bf16 v[88:91], v[164:167], v[176:179], v[88:91]
	v_mfma_f32_16x16x32_bf16 v[84:87], v[128:131], v[176:179], v[84:87]
	global_load_lds_dwordx4 v[170:171], off
	s_mov_b32 m0, s1
	s_waitcnt lgkmcnt(4)
	v_mfma_f32_16x16x32_bf16 v[64:67], v[156:159], v[180:183], v[64:67]
	v_mfma_f32_16x16x32_bf16 v[76:79], v[160:163], v[180:183], v[76:79]
	v_mfma_f32_16x16x32_bf16 v[72:75], v[164:167], v[180:183], v[72:75]
	v_mfma_f32_16x16x32_bf16 v[68:71], v[128:131], v[180:183], v[68:71]
	global_load_lds_dwordx4 v[168:169], off
	s_waitcnt lgkmcnt(3)
	v_mfma_f32_16x16x32_bf16 v[48:51], v[156:159], v[184:187], v[48:51]
	v_mfma_f32_16x16x32_bf16 v[60:63], v[160:163], v[184:187], v[60:63]
	v_mfma_f32_16x16x32_bf16 v[56:59], v[164:167], v[184:187], v[56:59]
	v_mfma_f32_16x16x32_bf16 v[52:55], v[128:131], v[184:187], v[52:55]
	s_waitcnt lgkmcnt(2)
	v_mfma_f32_16x16x32_bf16 v[32:35], v[156:159], v[188:191], v[32:35]
	v_mfma_f32_16x16x32_bf16 v[44:47], v[160:163], v[188:191], v[44:47]
	v_mfma_f32_16x16x32_bf16 v[40:43], v[164:167], v[188:191], v[40:43]
	v_mfma_f32_16x16x32_bf16 v[36:39], v[128:131], v[188:191], v[36:39]
	s_waitcnt lgkmcnt(1)
	v_mfma_f32_16x16x32_bf16 v[12:15], v[156:159], v[192:195], v[12:15]
	v_mfma_f32_16x16x32_bf16 v[24:27], v[160:163], v[192:195], v[24:27]
	v_mfma_f32_16x16x32_bf16 v[20:23], v[164:167], v[192:195], v[20:23]
	v_mfma_f32_16x16x32_bf16 v[16:19], v[128:131], v[192:195], v[16:19]
	s_waitcnt lgkmcnt(0)
	v_mfma_f32_16x16x32_bf16 v[0:3], v[156:159], v[196:199], v[0:3]
	s_waitcnt vmcnt(0)
	s_barrier
; DI unsigned pk2(float a, float b) { f2_t v = {a, b}; bf2_t r = __builtin_convertvector(v, bf2_t); return __builtin_bit_cast(unsigned, r); }
; #define G3_LDA(buf, kt, i) __builtin_amdgcn_global_load_lds((const unsigned*)(ga + (size_t)((i) * 64) * lda + (kt) * 64), (lds_u32*)(sdst + (buf) * STAGE + (i) * 8192), 16, 0, 0)
; #define G3_LDB(buf, kt, i) __builtin_amdgcn_global_load_lds((const unsigned*)(gb + (size_t)((i) * 64) * ldb + (kt) * 64), (lds_u32*)(sdst + (buf) * STAGE + B_OFF + (i) * 8192), 16, 0, 0)
; DI void gemm3_mainloop(const int wave8, const int lane, const bf16_t* __restrict__ A, int lda, const bf16_t* __restrict__ Bt, int ldb, int K,
;                        unsigned char* smem, f32x4 (&acc)[8][4]) {
;     ...
;     asm volatile("s_waitcnt vmcnt(0)" ::: "memory");
;     G3_LDA(0, 0, 0); G3_LDA(0, 0, 1); G3_LDA(0, 0, 2); G3_LDA(0, 0, 3); G3_LDB(0, 0, 0); G3_LDB(0, 0, 1); G3_LDB(0, 0, 2); G3_LDB(0, 0, 3);
;     asm volatile("s_waitcnt vmcnt(0)" ::: "memory");
;     __builtin_amdgcn_s_barrier();
;     for (int kt = 0; kt < nk; kt += 2) { G3_STEP(0, 1, kt); G3_STEP(1, 0, kt + 1); }
; DI void phase1(const Params& p, unsigned char* smem) {
;     ...
;         const int c128 = nt * 2 + (wn >> 1);
;         if (c128 >= 47) return;
;         bf16_t* dst; int ld, c0;
;         if (c128 < 23) { dst = pa; ld = LDPA; c0 = c128 * 128; } else { dst = pb; ld = LDPB; c0 = (c128 - 23) * 128; }
; #pragma unroll
;         for (int i = 0; i < 8; ++i) {
;             const int m = mt * 256 + wm * 128 + i * 16 + fr;
;             float ss = 0.f;
; #pragma unroll
;             for (int j = 0; j < 4; ++j) {
;                 const f32x4 v = acc[i][j];
;                 ss += v.x * v.x + v.y * v.y + v.z * v.z + v.w * v.w;
;                 u32x2 o; o.x = pk2(v.x, v.y); o.y = pk2(v.z, v.w);
;                 *(u32x2*)(dst + (size_t)m * ld + c0 + (wn & 1) * 64 + j * 16 + fq * 4) = o;
;             }
;             if (c128 < 6) {
;                 ss += __shfl_xor(ss, 16); ss += __shfl_xor(ss, 32);
;                 if (fq == 0) atomicAdd(ssq + (c128 < 4 ? 0 : T_) + m, ss);
	ds_read_b128 v[168:171], v149
	ds_read_b128 v[156:159], v148 offset:34816
	ds_read_b128 v[172:175], v149 offset:2048
	ds_read_b128 v[176:179], v149 offset:4096
	ds_read_b128 v[180:183], v149 offset:6144
	ds_read_b128 v[184:187], v149 offset:8192
	ds_read_b128 v[188:191], v149 offset:10240
	ds_read_b128 v[192:195], v149 offset:12288
	v_mfma_f32_16x16x32_bf16 v[8:11], v[160:163], v[196:199], v[8:11]
	v_mfma_f32_16x16x32_bf16 v[4:7], v[164:167], v[196:199], v[4:7]
	v_mfma_f32_16x16x32_bf16 v[28:31], v[128:131], v[196:199], v[28:31]
	s_cbranch_vccnz .LBB0_90
	s_waitcnt lgkmcnt(0)
	s_lshl_b32 s5, s5, 1
	s_or_b32 s36, s5, s44
	s_cmp_gt_i32 s36, 46
	s_cbranch_scc1 .LBB0_88
	s_lshl_b32 s5, s36, 7
	s_add_i32 s6, s5, 0xfffff480
	s_cmp_lt_i32 s36, 23
	s_cselect_b32 s6, s5, s6
	s_cselect_b32 s5, s48, 0xddc5000
	s_cselect_b32 s75, s46, 0xc00
	s_add_u32 s8, s72, s5
	s_addc_u32 s9, s73, 0
	s_lshl_b32 s4, s4, 8
	s_add_i32 s4, s4, s54
	s_ashr_i32 s7, s6, 31
	v_and_or_b32 v130, v147, 15, s4
	s_lshl_b64 s[4:5], s[6:7], 1
	s_add_u32 s4, s8, s4
	s_addc_u32 s5, s9, s5
	s_add_u32 s4, s4, s49
	s_addc_u32 s5, s5, 0
	v_lshlrev_b32_e32 v132, 3, v145
	v_lshl_add_u64 v[128:129], s[4:5], 0, v[132:133]
	v_mov_b32_e32 v132, v130
	v_mad_u64_u32 v[130:131], s[4:5], s75, v130, 0
	v_lshl_add_u64 v[130:131], v[130:131], 1, v[128:129]
	v_cvt_pk_bf16_f32 v134, v112, v113
	v_cvt_pk_bf16_f32 v135, v114, v115
	s_cmp_lt_i32 s36, 6
	global_store_dwordx2 v[130:131], v[134:135], off
	v_cvt_pk_bf16_f32 v134, v124, v125
	v_cvt_pk_bf16_f32 v135, v126, v127
	s_cselect_b64 s[6:7], -1, 0
	s_cmp_lt_i32 s36, 4
	global_store_dwordx2 v[130:131], v[134:135], off offset:32
	v_cvt_pk_bf16_f32 v134, v120, v121
	v_cvt_pk_bf16_f32 v135, v122, v123
	s_cselect_b32 s18, 0, 0x8000
	s_cmp_gt_i32 s36, 5
	v_cmp_gt_u32_e64 s[8:9], 16, v146
	global_store_dwordx2 v[130:131], v[134:135], off offset:64
	v_cvt_pk_bf16_f32 v134, v116, v117
	v_cvt_pk_bf16_f32 v135, v118, v119
	global_store_dwordx2 v[130:131], v[134:135], off offset:96
	s_cbranch_scc1 .LBB0_96
	v_mul_f32_e32 v130, v113, v113
	v_mul_f32_e32 v125, v125, v125
	v_fmac_f32_e32 v130, v112, v112
	v_fmac_f32_e32 v125, v124, v124
	v_mul_f32_e32 v121, v121, v121
	v_fmac_f32_e32 v130, v114, v114
	v_fmac_f32_e32 v125, v126, v126
	v_fmac_f32_e32 v121, v120, v120
	v_mul_f32_e32 v117, v117, v117
	v_fmac_f32_e32 v130, v115, v115
	v_fmac_f32_e32 v125, v127, v127
	v_fmac_f32_e32 v121, v122, v122
	v_fmac_f32_e32 v117, v116, v116
	v_add_f32_e32 v124, v130, v125
	v_fmac_f32_e32 v121, v123, v123
	v_fmac_f32_e32 v117, v118, v118
	v_add_f32_e32 v120, v124, v121
	v_fmac_f32_e32 v117, v119, v119
	v_add_f32_e32 v116, v120, v117
	ds_bpermute_b32 v117, v144, v116
	s_waitcnt lgkmcnt(0)
	v_add_f32_e32 v116, v116, v117
	ds_bpermute_b32 v117, v241, v116
	s_and_saveexec_b64 s[4:5], s[8:9]
	s_cbranch_execz .LBB0_95
	s_lshl_b32 s37, s18, 2
	s_add_u32 s76, s12, s37
	s_addc_u32 s77, s13, 0
	s_waitcnt lgkmcnt(0)
	v_add_f32_e32 v118, v116, v117
	v_lshl_add_u64 v[116:117], v[132:133], 2, s[76:77]
	global_atomic_add_f32 v[116:117], v118, off

; DI int fresh_tid(const Params& p) { int t = p.wave_u * 64 + (int)__builtin_amdgcn_mbcnt_hi(~0u, __builtin_amdgcn_mbcnt_lo(~0u, 0u)); asm volatile("" : "+v"(t)); return t; }
; #define G3_LDA(buf, kt, i) __builtin_amdgcn_global_load_lds((const unsigned*)(ga + (size_t)((i) * 64) * lda + (kt) * 64), (lds_u32*)(sdst + (buf) * STAGE + (i) * 8192), 16, 0, 0)
; #define G3_LDB(buf, kt, i) __builtin_amdgcn_global_load_lds((const unsigned*)(gb + (size_t)((i) * 64) * ldb + (kt) * 64), (lds_u32*)(sdst + (buf) * STAGE + B_OFF + (i) * 8192), 16, 0, 0)
; DI void gemm3_mainloop(const int wave8, const int lane, const bf16_t* __restrict__ A, int lda, const bf16_t* __restrict__ Bt, int ldb, int K,
;                        unsigned char* smem, f32x4 (&acc)[8][4]) {
;     constexpr int STAGE = 512 * 128, B_OFF = 256 * 128;
;     const int fr = lane & 15, fq = lane >> 4, wm = wave8 >> 2, wn = wave8 & 3;
;     const int t512 = wave8 * 64 + lane;
; #pragma unroll
;     for (int i = 0; i < 8; ++i)
; #pragma unroll
;         for (int j = 0; j < 4; ++j) acc[i][j] = (f32x4){0.f, 0.f, 0.f, 0.f};
;     const int nk = K / 64;
;     const int srow = t512 >> 3, ssc = (t512 & 7) ^ ((srow >> 1) & 7);
;     const bf16_t* ga = A + (size_t)srow * lda + ssc * 8;
;     const bf16_t* gb = Bt + (size_t)srow * ldb + ssc * 8;
;     unsigned char* sdst = smem + wave8 * 1024;
;     ...
;     const int sw = (fr >> 1) & 7;
;     ...
;     asm volatile("s_waitcnt vmcnt(0)" ::: "memory");
;     G3_LDA(0, 0, 0); G3_LDA(0, 0, 1); G3_LDA(0, 0, 2); G3_LDA(0, 0, 3); G3_LDB(0, 0, 0); G3_LDB(0, 0, 1); G3_LDB(0, 0, 2); G3_LDB(0, 0, 3);
;     asm volatile("s_waitcnt vmcnt(0)" ::: "memory");
;     __builtin_amdgcn_s_barrier();
; DI void phase4(const Params& p, unsigned char* smem) {
;     ...
;     for_tiles3(T_ / 256, 2048 / 256, [&](int mt, int nt) {
;         const int lane = fresh_tid(p) & 63, fr = lane & 15, fq = lane >> 4, wm = p.wave8 >> 2, wn = p.wave8 & 3;
;         f32x4 acc[8][4];
;         gemm3_mainloop(p.wave8, lane, mixed + (size_t)mt * 256 * LDK, LDK, wt + (size_t)nt * 256 * LDK, LDK, 2048, smem, acc);
.LBB0_502:
	s_and_b32 s45, s44, 7
	v_mov_b32_e32 v138, v227
	s_and_b32 s2, s37, 7
	s_or_b32 s46, s45, s35
	s_ashr_i32 s45, s44, 3
	s_add_i32 s2, s30, s2
	v_and_b32_e32 v2, 63, v138
	s_add_i32 s45, s45, s36
	s_mul_i32 s48, s46, 0x108000
	v_or_b32_e32 v0, s86, v2
	s_add_u32 s48, s42, s48
	v_lshrrev_b32_e32 v5, 4, v0
	s_addc_u32 s49, s43, 0
	s_mul_i32 s53, s45, 0x108000
	v_bitop3_b32 v6, v5, v138, 63 bitop3:0x78
	s_mul_hi_i32 s52, s45, 0x108000
	s_add_u32 s50, s28, s53
	v_ashrrev_i32_e32 v4, 3, v0
	v_mov_b64_e32 v[0:1], s[48:49]
	v_lshlrev_b32_e32 v6, 4, v6
	s_addc_u32 s51, s29, s52
	v_mad_i64_i32 v[0:1], s[48:49], v4, s31, v[0:1]
	v_and_b32_e32 v128, 0x70, v6
	v_lshl_add_u64 v[130:131], v[0:1], 0, v[128:129]
	v_mov_b64_e32 v[0:1], s[50:51]
	s_mov_b32 m0, s0
	v_mad_i64_i32 v[0:1], s[48:49], v4, s31, v[0:1]
	s_waitcnt vmcnt(0)
	v_lshl_add_u64 v[132:133], v[0:1], 0, v[128:129]
	global_load_lds_dwordx4 v[130:131], off
	v_lshl_add_u64 v[0:1], v[130:131], 0, s[4:5]
	s_mov_b32 m0, s55
	v_bfe_u32 v3, v138, 4, 2
	global_load_lds_dwordx4 v[0:1], off
	v_lshl_add_u64 v[0:1], v[130:131], 0, s[6:7]
	s_mov_b32 m0, s87
	v_lshrrev_b32_e32 v6, 1, v138
	global_load_lds_dwordx4 v[0:1], off
	v_lshl_add_u64 v[0:1], v[130:131], 0, s[8:9]
	s_mov_b32 m0, s69
	v_bfe_u32 v7, v138, 1, 3
	global_load_lds_dwordx4 v[0:1], off
	s_mov_b32 m0, s68
	v_lshl_add_u64 v[0:1], v[132:133], 0, s[4:5]
	global_load_lds_dwordx4 v[132:133], off
	s_mov_b32 m0, s39
	s_mul_hi_u32 s47, s2, 0x108000
	global_load_lds_dwordx4 v[0:1], off
	v_lshl_add_u64 v[0:1], v[132:133], 0, s[6:7]
	s_mov_b32 m0, s38
	s_mul_i32 s2, s2, 0x108000
	global_load_lds_dwordx4 v[0:1], off
	v_lshl_add_u64 v[0:1], v[132:133], 0, s[8:9]
	s_mov_b32 m0, s1
	s_add_u32 s48, s72, s2
	global_load_lds_dwordx4 v[0:1], off
	v_bitop3_b32 v0, v6, v3, 7 bitop3:0x6c
	v_lshlrev_b32_e32 v0, 4, v0
	v_add_u32_e32 v6, 0, v0
	v_bitop3_b32 v1, v3, v7, 4 bitop3:0x36
	v_add_u32_e32 v7, s83, v0
	v_add_u32_e32 v8, s34, v0
	v_lshlrev_b32_e32 v0, 7, v138
	v_and_b32_e32 v0, 0x780, v0
	v_lshlrev_b32_e32 v1, 4, v1
	v_or_b32_e32 v11, s90, v0
	v_or_b32_e32 v12, s91, v0
	v_bitop3_b32 v0, v5, 7, v2 bitop3:0x48
	s_addc_u32 s49, s73, s47
	v_add_u32_e32 v3, 0, v1
	v_add_u32_e32 v9, s83, v1
	v_add_u32_e32 v10, s34, v1
	v_lshlrev_b32_e32 v128, 4, v0
	v_mov_b64_e32 v[0:1], s[48:49]
	v_mad_i64_i32 v[134:135], s[48:49], v4, s31, v[0:1]
	s_add_u32 s48, s72, s53
	s_waitcnt vmcnt(0)
	s_addc_u32 s49, s73, s52
	v_mov_b64_e32 v[0:1], s[48:49]
	v_mov_b32_e32 v32, 0
	v_mad_i64_i32 v[136:137], s[48:49], v4, s31, v[0:1]
	s_mov_b32 s2, 0
	v_add_u32_e32 v139, v6, v11
	v_add_u32_e32 v140, v6, v12
	v_add_u32_e32 v141, v3, v11
	v_add_u32_e32 v142, v3, v12
	v_add_u32_e32 v143, v7, v11
	v_add_u32_e32 v144, v8, v12
	v_add_u32_e32 v145, v9, v11
	v_add_u32_e32 v146, v10, v12
	v_mov_b32_e32 v33, v32
	v_mov_b32_e32 v34, v32
	v_mov_b32_e32 v35, v32
	v_mov_b32_e32 v0, v32
	v_mov_b32_e32 v1, v32
	v_mov_b32_e32 v2, v32
	v_mov_b32_e32 v3, v32
	v_mov_b32_e32 v4, v32
	v_mov_b32_e32 v5, v32
	v_mov_b32_e32 v6, v32
	v_mov_b32_e32 v7, v32
	v_mov_b32_e32 v8, v32
	v_mov_b32_e32 v9, v32
	v_mov_b32_e32 v10, v32
	v_mov_b32_e32 v11, v32
	v_mov_b32_e32 v12, v32
	v_mov_b32_e32 v13, v32
	v_mov_b32_e32 v14, v32
	v_mov_b32_e32 v15, v32
	v_mov_b32_e32 v16, v32
	v_mov_b32_e32 v17, v32
	v_mov_b32_e32 v18, v32
	v_mov_b32_e32 v19, v32
	v_mov_b32_e32 v20, v32
	v_mov_b32_e32 v21, v32
	v_mov_b32_e32 v22, v32
	v_mov_b32_e32 v23, v32
	v_mov_b32_e32 v24, v32
	v_mov_b32_e32 v25, v32
	v_mov_b32_e32 v26, v32
	v_mov_b32_e32 v27, v32
	v_mov_b32_e32 v28, v32
	v_mov_b32_e32 v29, v32
	v_mov_b32_e32 v30, v32
	v_mov_b32_e32 v31, v32
	v_mov_b32_e32 v36, v32
	v_mov_b32_e32 v37, v32
	v_mov_b32_e32 v38, v32
	v_mov_b32_e32 v39, v32
	v_mov_b32_e32 v40, v32
	v_mov_b32_e32 v41, v32
	v_mov_b32_e32 v42, v32
	v_mov_b32_e32 v43, v32
	v_mov_b32_e32 v44, v32
	v_mov_b32_e32 v45, v32
	v_mov_b32_e32 v46, v32
	v_mov_b32_e32 v47, v32
	v_mov_b32_e32 v48, v32
	v_mov_b32_e32 v49, v32
	v_mov_b32_e32 v50, v32
	v_mov_b32_e32 v51, v32
	v_mov_b32_e32 v52, v32
	v_mov_b32_e32 v53, v32
	v_mov_b32_e32 v54, v32
	v_mov_b32_e32 v55, v32
	v_mov_b32_e32 v56, v32
	v_mov_b32_e32 v57, v32
	v_mov_b32_e32 v58, v32
	v_mov_b32_e32 v59, v32
	v_mov_b32_e32 v60, v32
	v_mov_b32_e32 v61, v32
	v_mov_b32_e32 v62, v32
	v_mov_b32_e32 v63, v32
	v_mov_b32_e32 v64, v32
	v_mov_b32_e32 v65, v32
	v_mov_b32_e32 v66, v32
	v_mov_b32_e32 v67, v32
	v_mov_b32_e32 v68, v32
	v_mov_b32_e32 v69, v32
	v_mov_b32_e32 v70, v32
	v_mov_b32_e32 v71, v32
	v_mov_b32_e32 v72, v32
	v_mov_b32_e32 v73, v32
	v_mov_b32_e32 v74, v32
	v_mov_b32_e32 v75, v32
	v_mov_b32_e32 v76, v32
	v_mov_b32_e32 v77, v32
	v_mov_b32_e32 v78, v32
	v_mov_b32_e32 v79, v32
	v_mov_b32_e32 v80, v32
	v_mov_b32_e32 v81, v32
	v_mov_b32_e32 v82, v32
	v_mov_b32_e32 v83, v32
	v_mov_b32_e32 v84, v32
	v_mov_b32_e32 v85, v32
	v_mov_b32_e32 v86, v32
	v_mov_b32_e32 v87, v32
	v_mov_b32_e32 v88, v32
	v_mov_b32_e32 v89, v32
	v_mov_b32_e32 v90, v32
	v_mov_b32_e32 v91, v32
	v_mov_b32_e32 v92, v32
	v_mov_b32_e32 v93, v32
	v_mov_b32_e32 v94, v32
	v_mov_b32_e32 v95, v32
	v_mov_b32_e32 v96, v32
	v_mov_b32_e32 v97, v32
	v_mov_b32_e32 v98, v32
	v_mov_b32_e32 v99, v32
	v_mov_b32_e32 v100, v32
	v_mov_b32_e32 v101, v32
	v_mov_b32_e32 v102, v32
	v_mov_b32_e32 v103, v32
	v_mov_b32_e32 v104, v32
	v_mov_b32_e32 v105, v32
	v_mov_b32_e32 v106, v32
	v_mov_b32_e32 v107, v32
	v_mov_b32_e32 v108, v32
	v_mov_b32_e32 v109, v32
	v_mov_b32_e32 v110, v32
	v_mov_b32_e32 v111, v32
	v_mov_b32_e32 v112, v32
	v_mov_b32_e32 v113, v32
	v_mov_b32_e32 v114, v32
	v_mov_b32_e32 v115, v32
	v_mov_b32_e32 v116, v32
	v_mov_b32_e32 v117, v32
	v_mov_b32_e32 v118, v32
	v_mov_b32_e32 v119, v32
	v_mov_b32_e32 v120, v32
	v_mov_b32_e32 v121, v32
	v_mov_b32_e32 v122, v32
	v_mov_b32_e32 v123, v32
	v_mov_b32_e32 v124, v32
	v_mov_b32_e32 v125, v32
	v_mov_b32_e32 v126, v32
	v_mov_b32_e32 v127, v32
	s_barrier
	ds_read_b128 v[148:151], v139 offset:32768
	ds_read_b128 v[164:167], v140
	ds_read_b128 v[168:171], v140 offset:2048
	ds_read_b128 v[172:175], v140 offset:4096
	ds_read_b128 v[176:179], v140 offset:6144
	ds_read_b128 v[180:183], v140 offset:8192
	ds_read_b128 v[184:187], v140 offset:10240
	ds_read_b128 v[188:191], v140 offset:12288
; DI void gemm3_mainloop(const int wave8, const int lane, const bf16_t* __restrict__ A, int lda, const bf16_t* __restrict__ Bt, int ldb, int K,
;                        unsigned char* smem, f32x4 (&acc)[8][4]) {
;     ...
;     const int sw = (fr >> 1) & 7;
.LBB0_503:
	ds_read_b128 v[152:155], v139 offset:34816
	ds_read_b128 v[156:159], v139 offset:36864
	ds_read_b128 v[160:163], v139 offset:38912
	ds_read_b128 v[192:195], v140 offset:14336
	v_lshl_add_u64 v[196:197], v[134:135], 0, v[128:129]
	s_mov_b32 m0, s88
	s_waitcnt lgkmcnt(10)
	v_mfma_f32_16x16x32_bf16 v[124:127], v[148:151], v[164:167], v[124:127]
	s_add_i32 s50, s2, 1
	s_add_i32 s47, s2, 2
	s_cmp_lt_u32 s2, 30
	s_waitcnt lgkmcnt(3)
	v_mfma_f32_16x16x32_bf16 v[120:123], v[152:155], v[164:167], v[120:123]
	s_cselect_b64 s[48:49], -1, 0
	s_and_b64 vcc, s[48:49], exec
	s_cselect_b32 s2, s47, s50
	s_waitcnt lgkmcnt(2)
	v_mfma_f32_16x16x32_bf16 v[116:119], v[156:159], v[164:167], v[116:119]
	s_lshl_b32 s2, s2, 7
	v_lshl_add_u64 v[134:135], v[134:135], 0, s[26:27]
	s_waitcnt lgkmcnt(1)
	v_mfma_f32_16x16x32_bf16 v[112:115], v[160:163], v[164:167], v[112:115]
	v_lshl_add_u64 v[164:165], v[196:197], 0, s[10:11]
	global_load_lds_dwordx4 v[164:165], off
	v_lshl_add_u64 v[164:165], v[196:197], 0, s[12:13]
	s_mov_b32 m0, s92
	v_mfma_f32_16x16x32_bf16 v[108:111], v[148:151], v[168:171], v[108:111]
	v_mfma_f32_16x16x32_bf16 v[104:107], v[152:155], v[168:171], v[104:107]
	v_mfma_f32_16x16x32_bf16 v[100:103], v[156:159], v[168:171], v[100:103]
	v_mfma_f32_16x16x32_bf16 v[96:99], v[160:163], v[168:171], v[96:99]
	global_load_lds_dwordx4 v[164:165], off
	v_lshl_add_u64 v[164:165], v[196:197], 0, s[14:15]
	s_mov_b32 m0, s93
	v_mfma_f32_16x16x32_bf16 v[92:95], v[148:151], v[172:175], v[92:95]
	v_mfma_f32_16x16x32_bf16 v[88:91], v[152:155], v[172:175], v[88:91]
	v_mfma_f32_16x16x32_bf16 v[84:87], v[156:159], v[172:175], v[84:87]
	v_mfma_f32_16x16x32_bf16 v[80:83], v[160:163], v[172:175], v[80:83]
	global_load_lds_dwordx4 v[164:165], off
	v_lshl_add_u64 v[164:165], v[196:197], 0, s[16:17]
	s_mov_b32 m0, s94
	v_mfma_f32_16x16x32_bf16 v[76:79], v[148:151], v[176:179], v[76:79]
	v_lshl_add_u64 v[196:197], v[136:137], 0, v[128:129]
	v_lshl_add_u64 v[198:199], v[196:197], 0, s[18:19]
	v_lshl_add_u64 v[136:137], v[136:137], 0, s[26:27]
	v_mfma_f32_16x16x32_bf16 v[72:75], v[152:155], v[176:179], v[72:75]
	v_mfma_f32_16x16x32_bf16 v[68:71], v[156:159], v[176:179], v[68:71]
	v_mfma_f32_16x16x32_bf16 v[64:67], v[160:163], v[176:179], v[64:67]
	global_load_lds_dwordx4 v[164:165], off
	s_mov_b32 m0, s89
	v_mfma_f32_16x16x32_bf16 v[60:63], v[148:151], v[180:183], v[60:63]
	v_mfma_f32_16x16x32_bf16 v[56:59], v[152:155], v[180:183], v[56:59]
	v_mfma_f32_16x16x32_bf16 v[52:55], v[156:159], v[180:183], v[52:55]
	v_mfma_f32_16x16x32_bf16 v[48:51], v[160:163], v[180:183], v[48:51]
	v_mfma_f32_16x16x32_bf16 v[44:47], v[148:151], v[184:187], v[44:47]
	v_mfma_f32_16x16x32_bf16 v[40:43], v[152:155], v[184:187], v[40:43]
	v_mfma_f32_16x16x32_bf16 v[36:39], v[156:159], v[184:187], v[36:39]
	v_mfma_f32_16x16x32_bf16 v[28:31], v[160:163], v[184:187], v[28:31]
	v_mfma_f32_16x16x32_bf16 v[24:27], v[148:151], v[188:191], v[24:27]
	v_mfma_f32_16x16x32_bf16 v[20:23], v[152:155], v[188:191], v[20:23]
	v_mfma_f32_16x16x32_bf16 v[16:19], v[156:159], v[188:191], v[16:19]
	v_mfma_f32_16x16x32_bf16 v[12:15], v[160:163], v[188:191], v[12:15]
	s_waitcnt lgkmcnt(0)
	v_mfma_f32_16x16x32_bf16 v[8:11], v[148:151], v[192:195], v[8:11]
	v_mfma_f32_16x16x32_bf16 v[4:7], v[152:155], v[192:195], v[4:7]
	v_mfma_f32_16x16x32_bf16 v[0:3], v[156:159], v[192:195], v[0:3]
	v_mfma_f32_16x16x32_bf16 v[32:35], v[160:163], v[192:195], v[32:35]
	ds_read_b128 v[148:151], v141 offset:32768
	ds_read_b128 v[164:167], v142
	ds_read_b128 v[152:155], v141 offset:34816
	ds_read_b128 v[156:159], v141 offset:36864
	ds_read_b128 v[160:163], v141 offset:38912
	ds_read_b128 v[168:171], v142 offset:2048
	ds_read_b128 v[172:175], v142 offset:4096
	ds_read_b128 v[176:179], v142 offset:6144
	ds_read_b128 v[180:183], v142 offset:8192
	ds_read_b128 v[184:187], v142 offset:10240
	ds_read_b128 v[188:191], v142 offset:12288
	ds_read_b128 v[192:195], v142 offset:14336
	s_waitcnt lgkmcnt(10)
	v_mfma_f32_16x16x32_bf16 v[124:127], v[148:151], v[164:167], v[124:127]
	s_waitcnt lgkmcnt(9)
	v_mfma_f32_16x16x32_bf16 v[120:123], v[152:155], v[164:167], v[120:123]
	s_waitcnt lgkmcnt(8)
	v_mfma_f32_16x16x32_bf16 v[116:119], v[156:159], v[164:167], v[116:119]
	s_waitcnt lgkmcnt(7)
	v_mfma_f32_16x16x32_bf16 v[112:115], v[160:163], v[164:167], v[112:115]
	global_load_lds_dwordx4 v[198:199], off
	v_lshl_add_u64 v[164:165], v[196:197], 0, s[20:21]
	s_mov_b32 m0, s95
	s_waitcnt lgkmcnt(6)
	v_mfma_f32_16x16x32_bf16 v[108:111], v[148:151], v[168:171], v[108:111]
	v_mfma_f32_16x16x32_bf16 v[104:107], v[152:155], v[168:171], v[104:107]
	v_mfma_f32_16x16x32_bf16 v[100:103], v[156:159], v[168:171], v[100:103]
	v_mfma_f32_16x16x32_bf16 v[96:99], v[160:163], v[168:171], v[96:99]
	global_load_lds_dwordx4 v[164:165], off
	v_lshl_add_u64 v[164:165], v[196:197], 0, s[22:23]
	s_mov_b32 m0, s96
	s_waitcnt lgkmcnt(5)
	v_mfma_f32_16x16x32_bf16 v[92:95], v[148:151], v[172:175], v[92:95]
	v_mfma_f32_16x16x32_bf16 v[88:91], v[152:155], v[172:175], v[88:91]
	v_mfma_f32_16x16x32_bf16 v[84:87], v[156:159], v[172:175], v[84:87]
	v_mfma_f32_16x16x32_bf16 v[80:83], v[160:163], v[172:175], v[80:83]
	global_load_lds_dwordx4 v[164:165], off
	v_lshl_add_u64 v[164:165], v[196:197], 0, s[24:25]
	s_mov_b32 m0, s97
	s_waitcnt lgkmcnt(4)
	v_mfma_f32_16x16x32_bf16 v[76:79], v[148:151], v[176:179], v[76:79]
	v_lshl_add_u64 v[196:197], v[130:131], 0, s[2:3]
	v_mfma_f32_16x16x32_bf16 v[72:75], v[152:155], v[176:179], v[72:75]
	v_mfma_f32_16x16x32_bf16 v[68:71], v[156:159], v[176:179], v[68:71]
	v_mfma_f32_16x16x32_bf16 v[64:67], v[160:163], v[176:179], v[64:67]
	global_load_lds_dwordx4 v[164:165], off
	s_waitcnt lgkmcnt(3)
	v_mfma_f32_16x16x32_bf16 v[60:63], v[148:151], v[180:183], v[60:63]
	s_mov_b32 m0, s0
	v_mfma_f32_16x16x32_bf16 v[56:59], v[152:155], v[180:183], v[56:59]
	v_mfma_f32_16x16x32_bf16 v[52:55], v[156:159], v[180:183], v[52:55]
	v_mfma_f32_16x16x32_bf16 v[48:51], v[160:163], v[180:183], v[48:51]
	s_waitcnt lgkmcnt(2)
	v_mfma_f32_16x16x32_bf16 v[44:47], v[148:151], v[184:187], v[44:47]
	v_mfma_f32_16x16x32_bf16 v[40:43], v[152:155], v[184:187], v[40:43]
	v_mfma_f32_16x16x32_bf16 v[36:39], v[156:159], v[184:187], v[36:39]
	v_mfma_f32_16x16x32_bf16 v[28:31], v[160:163], v[184:187], v[28:31]
	s_waitcnt lgkmcnt(1)
	v_mfma_f32_16x16x32_bf16 v[24:27], v[148:151], v[188:191], v[24:27]
	v_mfma_f32_16x16x32_bf16 v[20:23], v[152:155], v[188:191], v[20:23]
	v_mfma_f32_16x16x32_bf16 v[16:19], v[156:159], v[188:191], v[16:19]
	v_mfma_f32_16x16x32_bf16 v[12:15], v[160:163], v[188:191], v[12:15]
	s_waitcnt lgkmcnt(0)
	v_mfma_f32_16x16x32_bf16 v[8:11], v[148:151], v[192:195], v[8:11]
	s_waitcnt vmcnt(0)
	s_barrier
; DI void gemm3_mainloop(const int wave8, const int lane, const bf16_t* __restrict__ A, int lda, const bf16_t* __restrict__ Bt, int ldb, int K,
;                        unsigned char* smem, f32x4 (&acc)[8][4]) {
;     ...
;     const int sw = (fr >> 1) & 7;
	ds_read_b128 v[148:151], v143
	ds_read_b128 v[164:167], v144
	ds_read_b128 v[168:171], v144 offset:2048
	ds_read_b128 v[172:175], v144 offset:4096
	ds_read_b128 v[176:179], v144 offset:6144
	ds_read_b128 v[180:183], v144 offset:8192
	ds_read_b128 v[184:187], v144 offset:10240
	ds_read_b128 v[188:191], v144 offset:12288
	v_mfma_f32_16x16x32_bf16 v[4:7], v[152:155], v[192:195], v[4:7]
	v_mfma_f32_16x16x32_bf16 v[0:3], v[156:159], v[192:195], v[0:3]
	v_mfma_f32_16x16x32_bf16 v[32:35], v[160:163], v[192:195], v[32:35]
	ds_read_b128 v[152:155], v143 offset:2048
	ds_read_b128 v[156:159], v143 offset:4096
	ds_read_b128 v[160:163], v143 offset:6144
	ds_read_b128 v[192:195], v144 offset:14336
	s_waitcnt lgkmcnt(10)
	v_mfma_f32_16x16x32_bf16 v[124:127], v[148:151], v[164:167], v[124:127]
	s_waitcnt lgkmcnt(3)
	v_mfma_f32_16x16x32_bf16 v[120:123], v[152:155], v[164:167], v[120:123]
	s_waitcnt lgkmcnt(2)
	v_mfma_f32_16x16x32_bf16 v[116:119], v[156:159], v[164:167], v[116:119]
	s_waitcnt lgkmcnt(1)
	v_mfma_f32_16x16x32_bf16 v[112:115], v[160:163], v[164:167], v[112:115]
	global_load_lds_dwordx4 v[196:197], off
	v_lshl_add_u64 v[164:165], v[196:197], 0, s[4:5]
	s_mov_b32 m0, s55
	v_mfma_f32_16x16x32_bf16 v[108:111], v[148:151], v[168:171], v[108:111]
	v_mfma_f32_16x16x32_bf16 v[104:107], v[152:155], v[168:171], v[104:107]
	v_mfma_f32_16x16x32_bf16 v[100:103], v[156:159], v[168:171], v[100:103]
	v_mfma_f32_16x16x32_bf16 v[96:99], v[160:163], v[168:171], v[96:99]
	global_load_lds_dwordx4 v[164:165], off
	v_lshl_add_u64 v[164:165], v[196:197], 0, s[6:7]
	s_mov_b32 m0, s87
	v_mfma_f32_16x16x32_bf16 v[92:95], v[148:151], v[172:175], v[92:95]
	v_mfma_f32_16x16x32_bf16 v[88:91], v[152:155], v[172:175], v[88:91]
	v_mfma_f32_16x16x32_bf16 v[84:87], v[156:159], v[172:175], v[84:87]
	v_mfma_f32_16x16x32_bf16 v[80:83], v[160:163], v[172:175], v[80:83]
	global_load_lds_dwordx4 v[164:165], off
	v_lshl_add_u64 v[164:165], v[196:197], 0, s[8:9]
	s_mov_b32 m0, s69
	v_mfma_f32_16x16x32_bf16 v[76:79], v[148:151], v[176:179], v[76:79]
	v_lshl_add_u64 v[196:197], v[132:133], 0, s[2:3]
	s_mov_b32 s2, s47
	v_mfma_f32_16x16x32_bf16 v[72:75], v[152:155], v[176:179], v[72:75]
	v_mfma_f32_16x16x32_bf16 v[68:71], v[156:159], v[176:179], v[68:71]
	v_mfma_f32_16x16x32_bf16 v[64:67], v[160:163], v[176:179], v[64:67]
	global_load_lds_dwordx4 v[164:165], off
	s_mov_b32 m0, s68
	v_mfma_f32_16x16x32_bf16 v[60:63], v[148:151], v[180:183], v[60:63]
	v_mfma_f32_16x16x32_bf16 v[56:59], v[152:155], v[180:183], v[56:59]
	v_mfma_f32_16x16x32_bf16 v[52:55], v[156:159], v[180:183], v[52:55]
	v_mfma_f32_16x16x32_bf16 v[48:51], v[160:163], v[180:183], v[48:51]
	v_mfma_f32_16x16x32_bf16 v[44:47], v[148:151], v[184:187], v[44:47]
	v_mfma_f32_16x16x32_bf16 v[40:43], v[152:155], v[184:187], v[40:43]
	v_mfma_f32_16x16x32_bf16 v[36:39], v[156:159], v[184:187], v[36:39]
	v_mfma_f32_16x16x32_bf16 v[28:31], v[160:163], v[184:187], v[28:31]
	v_mfma_f32_16x16x32_bf16 v[24:27], v[148:151], v[188:191], v[24:27]
	v_mfma_f32_16x16x32_bf16 v[20:23], v[152:155], v[188:191], v[20:23]
	v_mfma_f32_16x16x32_bf16 v[16:19], v[156:159], v[188:191], v[16:19]
	v_mfma_f32_16x16x32_bf16 v[12:15], v[160:163], v[188:191], v[12:15]
	s_waitcnt lgkmcnt(0)
	v_mfma_f32_16x16x32_bf16 v[8:11], v[148:151], v[192:195], v[8:11]
	v_mfma_f32_16x16x32_bf16 v[4:7], v[152:155], v[192:195], v[4:7]
	v_mfma_f32_16x16x32_bf16 v[0:3], v[156:159], v[192:195], v[0:3]
	v_mfma_f32_16x16x32_bf16 v[32:35], v[160:163], v[192:195], v[32:35]
	ds_read_b128 v[148:151], v145
	ds_read_b128 v[164:167], v146
	ds_read_b128 v[152:155], v145 offset:2048
	ds_read_b128 v[156:159], v145 offset:4096
	ds_read_b128 v[160:163], v145 offset:6144
	ds_read_b128 v[168:171], v146 offset:2048
	ds_read_b128 v[172:175], v146 offset:4096
	ds_read_b128 v[176:179], v146 offset:6144
	ds_read_b128 v[180:183], v146 offset:8192
	ds_read_b128 v[184:187], v146 offset:10240
	ds_read_b128 v[188:191], v146 offset:12288
	ds_read_b128 v[192:195], v146 offset:14336
	s_waitcnt lgkmcnt(10)
	v_mfma_f32_16x16x32_bf16 v[124:127], v[148:151], v[164:167], v[124:127]
	s_waitcnt lgkmcnt(9)
	v_mfma_f32_16x16x32_bf16 v[120:123], v[152:155], v[164:167], v[120:123]
	s_waitcnt lgkmcnt(8)
	v_mfma_f32_16x16x32_bf16 v[116:119], v[156:159], v[164:167], v[116:119]
	s_waitcnt lgkmcnt(7)
	v_mfma_f32_16x16x32_bf16 v[112:115], v[160:163], v[164:167], v[112:115]
	global_load_lds_dwordx4 v[196:197], off
	v_lshl_add_u64 v[164:165], v[196:197], 0, s[4:5]
	s_mov_b32 m0, s39
	s_waitcnt lgkmcnt(6)
	v_mfma_f32_16x16x32_bf16 v[108:111], v[148:151], v[168:171], v[108:111]
	v_mfma_f32_16x16x32_bf16 v[104:107], v[152:155], v[168:171], v[104:107]
	v_mfma_f32_16x16x32_bf16 v[100:103], v[156:159], v[168:171], v[100:103]
	v_mfma_f32_16x16x32_bf16 v[96:99], v[160:163], v[168:171], v[96:99]
	global_load_lds_dwordx4 v[164:165], off
	v_lshl_add_u64 v[164:165], v[196:197], 0, s[6:7]
	s_mov_b32 m0, s38
	s_waitcnt lgkmcnt(5)
	v_mfma_f32_16x16x32_bf16 v[92:95], v[148:151], v[172:175], v[92:95]
	v_mfma_f32_16x16x32_bf16 v[88:91], v[152:155], v[172:175], v[88:91]
	v_mfma_f32_16x16x32_bf16 v[84:87], v[156:159], v[172:175], v[84:87]
	v_mfma_f32_16x16x32_bf16 v[80:83], v[160:163], v[172:175], v[80:83]
	global_load_lds_dwordx4 v[164:165], off
	v_lshl_add_u64 v[164:165], v[196:197], 0, s[8:9]
	s_mov_b32 m0, s1
	s_waitcnt lgkmcnt(4)
	v_mfma_f32_16x16x32_bf16 v[76:79], v[148:151], v[176:179], v[76:79]
	v_mfma_f32_16x16x32_bf16 v[72:75], v[152:155], v[176:179], v[72:75]
	v_mfma_f32_16x16x32_bf16 v[68:71], v[156:159], v[176:179], v[68:71]
	v_mfma_f32_16x16x32_bf16 v[64:67], v[160:163], v[176:179], v[64:67]
	global_load_lds_dwordx4 v[164:165], off
	s_waitcnt lgkmcnt(3)
	v_mfma_f32_16x16x32_bf16 v[60:63], v[148:151], v[180:183], v[60:63]
	v_mfma_f32_16x16x32_bf16 v[56:59], v[152:155], v[180:183], v[56:59]
	v_mfma_f32_16x16x32_bf16 v[52:55], v[156:159], v[180:183], v[52:55]
	v_mfma_f32_16x16x32_bf16 v[48:51], v[160:163], v[180:183], v[48:51]
	s_waitcnt lgkmcnt(2)
	v_mfma_f32_16x16x32_bf16 v[44:47], v[148:151], v[184:187], v[44:47]
	v_mfma_f32_16x16x32_bf16 v[40:43], v[152:155], v[184:187], v[40:43]
	v_mfma_f32_16x16x32_bf16 v[36:39], v[156:159], v[184:187], v[36:39]
	v_mfma_f32_16x16x32_bf16 v[28:31], v[160:163], v[184:187], v[28:31]
	s_waitcnt lgkmcnt(1)
	v_mfma_f32_16x16x32_bf16 v[24:27], v[148:151], v[188:191], v[24:27]
	v_mfma_f32_16x16x32_bf16 v[20:23], v[152:155], v[188:191], v[20:23]
	v_mfma_f32_16x16x32_bf16 v[16:19], v[156:159], v[188:191], v[16:19]
	v_mfma_f32_16x16x32_bf16 v[12:15], v[160:163], v[188:191], v[12:15]
	s_waitcnt lgkmcnt(0)
	v_mfma_f32_16x16x32_bf16 v[8:11], v[148:151], v[192:195], v[8:11]
	s_waitcnt vmcnt(0)
	s_barrier
; #define G3_LDA(buf, kt, i) __builtin_amdgcn_global_load_lds((const unsigned*)(ga + (size_t)((i) * 64) * lda + (kt) * 64), (lds_u32*)(sdst + (buf) * STAGE + (i) * 8192), 16, 0, 0)
; #define G3_LDB(buf, kt, i) __builtin_amdgcn_global_load_lds((const unsigned*)(gb + (size_t)((i) * 64) * ldb + (kt) * 64), (lds_u32*)(sdst + (buf) * STAGE + B_OFF + (i) * 8192), 16, 0, 0)
; DI void gemm3_mainloop(const int wave8, const int lane, const bf16_t* __restrict__ A, int lda, const bf16_t* __restrict__ Bt, int ldb, int K,
;                        unsigned char* smem, f32x4 (&acc)[8][4]) {
;     ...
;     asm volatile("s_waitcnt vmcnt(0)" ::: "memory");
;     G3_LDA(0, 0, 0); G3_LDA(0, 0, 1); G3_LDA(0, 0, 2); G3_LDA(0, 0, 3); G3_LDB(0, 0, 0); G3_LDB(0, 0, 1); G3_LDB(0, 0, 2); G3_LDB(0, 0, 3);
;     asm volatile("s_waitcnt vmcnt(0)" ::: "memory");
;     __builtin_amdgcn_s_barrier();
;     for (int kt = 0; kt < nk; kt += 2) { G3_STEP(0, 1, kt); G3_STEP(1, 0, kt + 1); }
; DI void phase4(const Params& p, unsigned char* smem) {
;     ...
;         for (int i = 0; i < 8; ++i) {
;             const size_t m = (size_t)mt * 256 + wm * 128 + i * 16 + fr;
; #pragma unroll
;             for (int j = 0; j < 4; ++j) {
;                 const int c = nt * 256 + wn * 64 + j * 16 + fq * 4;
;                 const f32x4 xv = *(const f32x4*)(p.x + m * DM + c);
;                 *(f32x4*)(p.out + m * DM + c) = xv + acc[i][j];
;             }
;         }
	ds_read_b128 v[148:151], v139 offset:32768
	ds_read_b128 v[164:167], v140
	ds_read_b128 v[168:171], v140 offset:2048
	ds_read_b128 v[172:175], v140 offset:4096
	ds_read_b128 v[176:179], v140 offset:6144
	ds_read_b128 v[180:183], v140 offset:8192
	ds_read_b128 v[184:187], v140 offset:10240
	ds_read_b128 v[188:191], v140 offset:12288
	v_mfma_f32_16x16x32_bf16 v[4:7], v[152:155], v[192:195], v[4:7]
	v_mfma_f32_16x16x32_bf16 v[0:3], v[156:159], v[192:195], v[0:3]
	v_mfma_f32_16x16x32_bf16 v[32:35], v[160:163], v[192:195], v[32:35]
	s_cbranch_vccnz .LBB0_503
	s_waitcnt lgkmcnt(0)
	v_lshrrev_b32_e32 v130, 2, v138
	s_lshl_b32 s2, s46, 8
	v_and_b32_e32 v130, 12, v130
	s_add_i32 s2, s2, s54
	v_lshl_or_b32 v130, s45, 8, v130
	v_and_or_b32 v128, v138, 15, s2
	v_or_b32_e32 v132, s82, v130
	v_lshlrev_b64 v[130:131], 13, v[128:129]
	v_ashrrev_i32_e32 v133, 31, v132
	v_lshl_add_u64 v[134:135], s[40:41], 0, v[130:131]
	v_lshlrev_b64 v[132:133], 2, v[132:133]
	v_lshl_add_u64 v[138:139], v[134:135], 0, v[132:133]
	global_load_dwordx4 v[134:137], v[138:139], off
	v_lshl_add_u64 v[140:141], s[70:71], 0, v[130:131]
	v_lshl_add_u64 v[140:141], v[140:141], 0, v[132:133]
	s_lshr_b32 s2, s33, 3
	s_add_i32 s44, s44, s84
	s_add_i32 s37, s37, s2
	s_cmp_gt_i32 s44, 31
	s_waitcnt vmcnt(0)
	v_pk_add_f32 v[126:127], v[126:127], v[136:137]
	v_pk_add_f32 v[124:125], v[124:125], v[134:135]
	global_store_dwordx4 v[140:141], v[124:127], off
	global_load_dwordx4 v[124:127], v[138:139], off offset:64
	s_waitcnt vmcnt(0)
	v_pk_add_f32 v[122:123], v[122:123], v[126:127]
	v_pk_add_f32 v[120:121], v[120:121], v[124:125]
	global_store_dwordx4 v[140:141], v[120:123], off offset:64
	global_load_dwordx4 v[120:123], v[138:139], off offset:128
	s_waitcnt vmcnt(0)
	v_pk_add_f32 v[118:119], v[118:119], v[122:123]
	v_pk_add_f32 v[116:117], v[116:117], v[120:121]
	global_store_dwordx4 v[140:141], v[116:119], off offset:128
	global_load_dwordx4 v[116:119], v[138:139], off offset:192
	v_or_b32_e32 v120, 0x20000, v130
	v_mov_b32_e32 v121, v131
	v_lshl_add_u64 v[122:123], s[40:41], 0, v[120:121]
	v_lshl_add_u64 v[122:123], v[122:123], 0, v[132:133]
	s_waitcnt vmcnt(0)
	v_pk_add_f32 v[114:115], v[114:115], v[118:119]
	v_pk_add_f32 v[112:113], v[112:113], v[116:117]
	global_store_dwordx4 v[140:141], v[112:115], off offset:192
	global_load_dwordx4 v[112:115], v[122:123], off
	v_lshl_add_u64 v[116:117], s[70:71], 0, v[120:121]
	v_lshl_add_u64 v[116:117], v[116:117], 0, v[132:133]
	s_waitcnt vmcnt(0)
	v_pk_add_f32 v[110:111], v[110:111], v[114:115]
	v_pk_add_f32 v[108:109], v[108:109], v[112:113]
	global_store_dwordx4 v[116:117], v[108:111], off
	global_load_dwordx4 v[108:111], v[122:123], off offset:64
	s_waitcnt vmcnt(0)
	v_pk_add_f32 v[106:107], v[106:107], v[110:111]
	v_pk_add_f32 v[104:105], v[104:105], v[108:109]
	global_store_dwordx4 v[116:117], v[104:107], off offset:64
	global_load_dwordx4 v[104:107], v[122:123], off offset:128
	s_waitcnt vmcnt(0)
	v_pk_add_f32 v[102:103], v[102:103], v[106:107]
	v_pk_add_f32 v[100:101], v[100:101], v[104:105]
	global_store_dwordx4 v[116:117], v[100:103], off offset:128
	global_load_dwordx4 v[100:103], v[122:123], off offset:192
	v_or_b32_e32 v104, 0x40000, v130
	v_mov_b32_e32 v105, v131
	v_lshl_add_u64 v[106:107], s[40:41], 0, v[104:105]
	v_lshl_add_u64 v[106:107], v[106:107], 0, v[132:133]
	s_waitcnt vmcnt(0)
	v_pk_add_f32 v[98:99], v[98:99], v[102:103]
	v_pk_add_f32 v[96:97], v[96:97], v[100:101]
	global_store_dwordx4 v[116:117], v[96:99], off offset:192
	global_load_dwordx4 v[96:99], v[106:107], off
	v_lshl_add_u64 v[100:101], s[70:71], 0, v[104:105]
	v_lshl_add_u64 v[100:101], v[100:101], 0, v[132:133]
	s_waitcnt vmcnt(0)
	v_pk_add_f32 v[94:95], v[94:95], v[98:99]
	v_pk_add_f32 v[92:93], v[92:93], v[96:97]
	global_store_dwordx4 v[100:101], v[92:95], off
	global_load_dwordx4 v[92:95], v[106:107], off offset:64
	s_waitcnt vmcnt(0)
	v_pk_add_f32 v[90:91], v[90:91], v[94:95]
	v_pk_add_f32 v[88:89], v[88:89], v[92:93]
	global_store_dwordx4 v[100:101], v[88:91], off offset:64
	global_load_dwordx4 v[88:91], v[106:107], off offset:128
	s_waitcnt vmcnt(0)
	v_pk_add_f32 v[86:87], v[86:87], v[90:91]
	v_pk_add_f32 v[84:85], v[84:85], v[88:89]
	global_store_dwordx4 v[100:101], v[84:87], off offset:128
	global_load_dwordx4 v[84:87], v[106:107], off offset:192
	v_or_b32_e32 v88, 0x60000, v130
	v_mov_b32_e32 v89, v131
	v_lshl_add_u64 v[90:91], s[40:41], 0, v[88:89]
	v_lshl_add_u64 v[90:91], v[90:91], 0, v[132:133]
	s_waitcnt vmcnt(0)
	v_pk_add_f32 v[82:83], v[82:83], v[86:87]
	v_pk_add_f32 v[80:81], v[80:81], v[84:85]
	global_store_dwordx4 v[100:101], v[80:83], off offset:192
	global_load_dwordx4 v[80:83], v[90:91], off
	v_lshl_add_u64 v[84:85], s[70:71], 0, v[88:89]
	v_lshl_add_u64 v[84:85], v[84:85], 0, v[132:133]
	s_waitcnt vmcnt(0)
	v_pk_add_f32 v[78:79], v[78:79], v[82:83]
	v_pk_add_f32 v[76:77], v[76:77], v[80:81]
	global_store_dwordx4 v[84:85], v[76:79], off
	global_load_dwordx4 v[76:79], v[90:91], off offset:64
	s_waitcnt vmcnt(0)
; template <typename F> DI void for_tiles3(int MT, int NT, F f) {
;     ...
;     for (int sidx = xcd; sidx < nsn * nsm; sidx += 8) {
;         const int sm = sidx / nsn, sn = sidx % nsn;
;         for (int tl = slot; tl < 32; tl += slots) f(sm * 8 + (tl & 7), sn * 4 + (tl >> 3));
; DI void phase4(const Params& p, unsigned char* smem) {
;     ...
;         for (int i = 0; i < 8; ++i) {
;             const size_t m = (size_t)mt * 256 + wm * 128 + i * 16 + fr;
; #pragma unroll
;             for (int j = 0; j < 4; ++j) {
;                 const int c = nt * 256 + wn * 64 + j * 16 + fq * 4;
;                 const f32x4 xv = *(const f32x4*)(p.x + m * DM + c);
;                 *(f32x4*)(p.out + m * DM + c) = xv + acc[i][j];
;             }
;         }
;     });
	v_pk_add_f32 v[74:75], v[74:75], v[78:79]
	v_pk_add_f32 v[72:73], v[72:73], v[76:77]
	global_store_dwordx4 v[84:85], v[72:75], off offset:64
	global_load_dwordx4 v[72:75], v[90:91], off offset:128
	s_waitcnt vmcnt(0)
	v_pk_add_f32 v[70:71], v[70:71], v[74:75]
	v_pk_add_f32 v[68:69], v[68:69], v[72:73]
	global_store_dwordx4 v[84:85], v[68:71], off offset:128
	global_load_dwordx4 v[68:71], v[90:91], off offset:192
	v_or_b32_e32 v72, 0x80000, v130
	v_mov_b32_e32 v73, v131
	v_lshl_add_u64 v[74:75], s[40:41], 0, v[72:73]
	v_lshl_add_u64 v[74:75], v[74:75], 0, v[132:133]
	s_waitcnt vmcnt(0)
	v_pk_add_f32 v[66:67], v[66:67], v[70:71]
	v_pk_add_f32 v[64:65], v[64:65], v[68:69]
	global_store_dwordx4 v[84:85], v[64:67], off offset:192
	global_load_dwordx4 v[64:67], v[74:75], off
	v_lshl_add_u64 v[68:69], s[70:71], 0, v[72:73]
	v_lshl_add_u64 v[68:69], v[68:69], 0, v[132:133]
	s_waitcnt vmcnt(0)
	v_pk_add_f32 v[62:63], v[62:63], v[66:67]
	v_pk_add_f32 v[60:61], v[60:61], v[64:65]
	global_store_dwordx4 v[68:69], v[60:63], off
	global_load_dwordx4 v[60:63], v[74:75], off offset:64
	s_waitcnt vmcnt(0)
	v_pk_add_f32 v[58:59], v[58:59], v[62:63]
	v_pk_add_f32 v[56:57], v[56:57], v[60:61]
	global_store_dwordx4 v[68:69], v[56:59], off offset:64
	global_load_dwordx4 v[56:59], v[74:75], off offset:128
	s_waitcnt vmcnt(0)
	v_pk_add_f32 v[54:55], v[54:55], v[58:59]
	v_pk_add_f32 v[52:53], v[52:53], v[56:57]
	global_store_dwordx4 v[68:69], v[52:55], off offset:128
	global_load_dwordx4 v[52:55], v[74:75], off offset:192
	v_or_b32_e32 v56, 0xa0000, v130
	v_mov_b32_e32 v57, v131
	v_lshl_add_u64 v[58:59], s[40:41], 0, v[56:57]
	v_lshl_add_u64 v[58:59], v[58:59], 0, v[132:133]
	s_waitcnt vmcnt(0)
	v_pk_add_f32 v[50:51], v[50:51], v[54:55]
	v_pk_add_f32 v[48:49], v[48:49], v[52:53]
	global_store_dwordx4 v[68:69], v[48:51], off offset:192
	global_load_dwordx4 v[48:51], v[58:59], off
	v_lshl_add_u64 v[52:53], s[70:71], 0, v[56:57]
	v_lshl_add_u64 v[52:53], v[52:53], 0, v[132:133]
	s_waitcnt vmcnt(0)
	v_pk_add_f32 v[46:47], v[46:47], v[50:51]
	v_pk_add_f32 v[44:45], v[44:45], v[48:49]
	global_store_dwordx4 v[52:53], v[44:47], off
	global_load_dwordx4 v[44:47], v[58:59], off offset:64
	s_waitcnt vmcnt(0)
	v_pk_add_f32 v[42:43], v[42:43], v[46:47]
	v_pk_add_f32 v[40:41], v[40:41], v[44:45]
	global_store_dwordx4 v[52:53], v[40:43], off offset:64
	global_load_dwordx4 v[40:43], v[58:59], off offset:128
	s_waitcnt vmcnt(0)
	v_pk_add_f32 v[38:39], v[38:39], v[42:43]
	v_pk_add_f32 v[36:37], v[36:37], v[40:41]
	global_store_dwordx4 v[52:53], v[36:39], off offset:128
	global_load_dwordx4 v[36:39], v[58:59], off offset:192
	v_or_b32_e32 v40, 0xc0000, v130
	v_mov_b32_e32 v41, v131
	v_lshl_add_u64 v[42:43], s[40:41], 0, v[40:41]
	v_lshl_add_u64 v[42:43], v[42:43], 0, v[132:133]
	v_or_b32_e32 v130, 0xe0000, v130
	s_waitcnt vmcnt(0)
	v_pk_add_f32 v[30:31], v[30:31], v[38:39]
	v_pk_add_f32 v[28:29], v[28:29], v[36:37]
	global_store_dwordx4 v[52:53], v[28:31], off offset:192
	global_load_dwordx4 v[28:31], v[42:43], off
	v_lshl_add_u64 v[36:37], s[70:71], 0, v[40:41]
	v_lshl_add_u64 v[36:37], v[36:37], 0, v[132:133]
	s_waitcnt vmcnt(0)
	v_pk_add_f32 v[26:27], v[26:27], v[30:31]
	v_pk_add_f32 v[24:25], v[24:25], v[28:29]
	global_store_dwordx4 v[36:37], v[24:27], off
	global_load_dwordx4 v[24:27], v[42:43], off offset:64
	s_waitcnt vmcnt(0)
	v_pk_add_f32 v[22:23], v[22:23], v[26:27]
	v_pk_add_f32 v[20:21], v[20:21], v[24:25]
	global_store_dwordx4 v[36:37], v[20:23], off offset:64
	global_load_dwordx4 v[20:23], v[42:43], off offset:128
	s_waitcnt vmcnt(0)
	v_pk_add_f32 v[18:19], v[18:19], v[22:23]
	v_pk_add_f32 v[16:17], v[16:17], v[20:21]
	global_store_dwordx4 v[36:37], v[16:19], off offset:128
	global_load_dwordx4 v[16:19], v[42:43], off offset:192
	v_lshl_add_u64 v[20:21], s[40:41], 0, v[130:131]
	v_lshl_add_u64 v[20:21], v[20:21], 0, v[132:133]
	s_waitcnt vmcnt(0)
	v_pk_add_f32 v[14:15], v[14:15], v[18:19]
	v_pk_add_f32 v[12:13], v[12:13], v[16:17]
	global_store_dwordx4 v[36:37], v[12:15], off offset:192
	global_load_dwordx4 v[12:15], v[20:21], off
	v_lshl_add_u64 v[16:17], s[70:71], 0, v[130:131]
	v_lshl_add_u64 v[16:17], v[16:17], 0, v[132:133]
	s_waitcnt vmcnt(0)
	v_pk_add_f32 v[10:11], v[10:11], v[14:15]
	v_pk_add_f32 v[8:9], v[8:9], v[12:13]
	global_store_dwordx4 v[16:17], v[8:11], off
	global_load_dwordx4 v[8:11], v[20:21], off offset:64
	s_waitcnt vmcnt(0)
	v_pk_add_f32 v[6:7], v[6:7], v[10:11]
	v_pk_add_f32 v[4:5], v[4:5], v[8:9]
	global_store_dwordx4 v[16:17], v[4:7], off offset:64
	global_load_dwordx4 v[4:7], v[20:21], off offset:128
	s_waitcnt vmcnt(0)
	v_pk_add_f32 v[2:3], v[2:3], v[6:7]
	v_pk_add_f32 v[0:1], v[0:1], v[4:5]
	global_store_dwordx4 v[16:17], v[0:3], off offset:128
	global_load_dwordx4 v[0:3], v[20:21], off offset:192
	s_waitcnt vmcnt(0)
	v_pk_add_f32 v[2:3], v[34:35], v[2:3]
	v_pk_add_f32 v[0:1], v[32:33], v[0:1]
	global_store_dwordx4 v[16:17], v[0:3], off offset:192
	s_cbranch_scc0 .LBB0_502
	s_branch .LBB0_499
